# grid barrier: non-leader workgroups poll the top-level generation word directly instead of the per-XCC one (one release hop fewer)
# speedup vs baseline: 1.0025x; 1.0014x over previous
; __device__ __forceinline__ unsigned xb_ld(unsigned* p)              { return __hip_atomic_load(p, __ATOMIC_RELAXED, __HIP_MEMORY_SCOPE_AGENT); }
; __device__ __forceinline__ unsigned xb_add(unsigned* p, unsigned v) { return __hip_atomic_fetch_add(p, v, __ATOMIC_RELAXED, __HIP_MEMORY_SCOPE_AGENT); }
; #define XB_SPIN(cond, bar) do { unsigned _sp = 0; while (cond) { __builtin_amdgcn_s_sleep(1); \
;     if ((++_sp & 255u) == 0u) { if (xb_ld(&(bar)[XB_TMO])) break; if (_sp > XB_SPIN_CAP) { atomicAdd(&(bar)[XB_TMO], 1u); break; } } } } while (0)
; __device__ __forceinline__ void xcd_barrier(const XcdBarrier& b) {
;     ...
;         const unsigned old = xb_add(&bar[XB_XSUB(b.x)], 1u);
;         const unsigned gen = old / nloc;
;         if (old + 1u == (gen + 1u) * nloc) {
;             __builtin_amdgcn_fence(__ATOMIC_RELEASE, "agent");
;             asm volatile("s_waitcnt vmcnt(0)" ::: "memory");
;             const unsigned og = xb_add(&bar[XB_TOP], 1u);
;             const unsigned tg = og / nx;
;             if (og + 1u == (tg + 1u) * nx) xb_add(&bar[XB_TOPGEN], 1u);
;             else XB_SPIN(xb_ld(&bar[XB_TOPGEN]) == tg, bar);
;             __builtin_amdgcn_fence(__ATOMIC_ACQUIRE, "agent");
;             xb_add(&bar[XB_XGEN(b.x)], 1u);
;             asm volatile("s_waitcnt vmcnt(0)" ::: "memory");
;         } else {
;             XB_SPIN(xb_ld(&bar[XB_XGEN(b.x)]) == gen, bar);
;             __builtin_amdgcn_fence(__ATOMIC_ACQUIRE, "agent");
;             asm volatile("s_waitcnt vmcnt(0)" ::: "memory");
.LBB0_204:
	s_or_b64 exec, exec, s[8:9]
	v_cvt_f32_u32_e32 v4, v2
	s_waitcnt vmcnt(0)
	v_readfirstlane_b32 s3, v3
	v_sub_u32_e32 v3, 0, v2
	v_rcp_iflag_f32_e32 v4, v4
	v_add_u32_e32 v5, s3, v1
	v_mul_f32_e32 v4, 0x4f7ffffe, v4
	v_cvt_u32_f32_e32 v4, v4
	v_mul_lo_u32 v1, v3, v4
	v_mul_hi_u32 v1, v4, v1
	v_add_u32_e32 v1, v4, v1
	v_mul_hi_u32 v1, v5, v1
	v_mul_lo_u32 v3, v1, v2
	v_sub_u32_e32 v3, v5, v3
	v_add_u32_e32 v4, 1, v1
	v_cmp_ge_u32_e32 vcc, v3, v2
	s_nop 1
	v_cndmask_b32_e32 v1, v1, v4, vcc
	v_sub_u32_e32 v4, v3, v2
	v_cndmask_b32_e32 v3, v3, v4, vcc
	v_add_u32_e32 v4, 1, v1
	v_cmp_ge_u32_e32 vcc, v3, v2
	v_add_u32_e32 v3, 1, v5
	s_nop 0
	v_cndmask_b32_e32 v1, v1, v4, vcc
	v_mul_lo_u32 v4, v2, v1
	v_add_u32_e32 v2, v4, v2
	v_cmp_ne_u32_e32 vcc, v3, v2
	s_and_saveexec_b64 s[6:7], vcc
	s_xor_b64 s[6:7], exec, s[6:7]
	s_cbranch_execz .LBB0_218
	s_waitcnt lgkmcnt(0)
	s_add_u32 s12, s26, 0xf500
	s_addc_u32 s13, s27, 0
	v_mov_b32_e32 v0, 0
	global_load_dword v0, v0, s[12:13] sc1
	s_waitcnt vmcnt(0)
	v_cmp_eq_u32_e32 vcc, v0, v1
	s_and_saveexec_b64 s[8:9], vcc
	s_cbranch_execz .LBB0_217
	s_add_u32 s10, s26, 0xc200
	s_addc_u32 s11, s27, 0
	s_mov_b32 s3, 1
	s_mov_b64 s[14:15], 0
	v_mov_b32_e32 v0, 0
	s_branch .LBB0_208
